# GLA scan sample loop software-pipelined: next iteration's three loads in flight under the current scan step (uniform vmcnt pattern, clamped last address)
# baseline (speedup 1.0000x reference)
.LBB0_4205:
	s_waitcnt vmcnt(22)
	v_add_co_u32_e32 v26, vcc, 0x4380000, v112
	s_mov_b32 s4, 0x4410000
	s_nop 0
	v_addc_co_u32_e32 v27, vcc, 0, v113, vcc
	v_cvt_pk_bf16_f32 v24, v168, v169
	v_cvt_pk_bf16_f32 v25, v170, v171
	s_waitcnt vmcnt(20)
	v_add_co_u32_e32 v30, vcc, s4, v112
	global_store_dwordx2 v[26:27], v[24:25], off
	v_lshlrev_b32_e32 v24, 16, v132
	v_and_b32_e32 v25, 0xffff0000, v132
	v_lshlrev_b32_e32 v26, 16, v133
	v_and_b32_e32 v27, 0xffff0000, v133
	v_addc_co_u32_e32 v31, vcc, 0, v113, vcc
	v_pk_fma_f32 v[26:27], v[34:35], v[170:171], v[26:27]
	v_pk_fma_f32 v[24:25], v[32:33], v[168:169], v[24:25]
	s_mov_b32 s4, 0x44a0000
	v_cvt_pk_bf16_f32 v28, v24, v25
	v_cvt_pk_bf16_f32 v29, v26, v27
	global_store_dwordx2 v[30:31], v[28:29], off
	v_lshlrev_b32_e32 v30, 16, v127
	v_and_b32_e32 v31, 0xffff0000, v127
	v_pk_fma_f32 v[22:23], v[22:23], v[26:27], v[30:31]
	v_add_co_u32_e32 v26, vcc, s4, v112
	v_lshlrev_b32_e32 v28, 16, v126
	v_and_b32_e32 v29, 0xffff0000, v126
	v_addc_co_u32_e32 v27, vcc, 0, v113, vcc
	v_pk_fma_f32 v[20:21], v[20:21], v[24:25], v[28:29]
	s_mov_b32 s4, 0x4530000
	v_cvt_pk_bf16_f32 v24, v20, v21
	v_cvt_pk_bf16_f32 v25, v22, v23
	global_store_dwordx2 v[26:27], v[24:25], off
	v_lshlrev_b32_e32 v26, 16, v123
	v_and_b32_e32 v27, 0xffff0000, v123
	v_pk_fma_f32 v[18:19], v[18:19], v[22:23], v[26:27]
	v_add_co_u32_e32 v22, vcc, s4, v112
	v_lshlrev_b32_e32 v24, 16, v122
	v_and_b32_e32 v25, 0xffff0000, v122
	v_addc_co_u32_e32 v23, vcc, 0, v113, vcc
	v_pk_fma_f32 v[16:17], v[16:17], v[20:21], v[24:25]
	s_mov_b32 s4, 0x45c0000
	v_cvt_pk_bf16_f32 v20, v16, v17
	v_cvt_pk_bf16_f32 v21, v18, v19
	global_store_dwordx2 v[22:23], v[20:21], off
	v_lshlrev_b32_e32 v22, 16, v121
	v_and_b32_e32 v23, 0xffff0000, v121
	v_pk_fma_f32 v[14:15], v[14:15], v[18:19], v[22:23]
	v_add_co_u32_e32 v18, vcc, s4, v112
	v_lshlrev_b32_e32 v20, 16, v120
	v_and_b32_e32 v21, 0xffff0000, v120
	v_addc_co_u32_e32 v19, vcc, 0, v113, vcc
	v_pk_fma_f32 v[12:13], v[12:13], v[16:17], v[20:21]
	s_mov_b32 s4, 0x4650000
	v_cvt_pk_bf16_f32 v16, v12, v13
	v_cvt_pk_bf16_f32 v17, v14, v15
	global_store_dwordx2 v[18:19], v[16:17], off
	v_lshlrev_b32_e32 v18, 16, v119
	v_and_b32_e32 v19, 0xffff0000, v119
	v_pk_fma_f32 v[10:11], v[10:11], v[14:15], v[18:19]
	v_add_co_u32_e32 v14, vcc, s4, v112
	v_lshlrev_b32_e32 v16, 16, v118
	v_and_b32_e32 v17, 0xffff0000, v118
	v_addc_co_u32_e32 v15, vcc, 0, v113, vcc
	v_pk_fma_f32 v[8:9], v[8:9], v[12:13], v[16:17]
	s_mov_b32 s4, 0x46e0000
	v_cvt_pk_bf16_f32 v12, v8, v9
	v_cvt_pk_bf16_f32 v13, v10, v11
	global_store_dwordx2 v[14:15], v[12:13], off
	v_lshlrev_b32_e32 v14, 16, v117
	v_and_b32_e32 v15, 0xffff0000, v117
	v_pk_fma_f32 v[6:7], v[6:7], v[10:11], v[14:15]
	v_add_co_u32_e32 v10, vcc, s4, v112
	v_lshlrev_b32_e32 v12, 16, v116
	v_and_b32_e32 v13, 0xffff0000, v116
	v_addc_co_u32_e32 v11, vcc, 0, v113, vcc
	v_pk_fma_f32 v[4:5], v[4:5], v[8:9], v[12:13]
	s_mov_b32 s4, 0x4770000
	v_cvt_pk_bf16_f32 v8, v4, v5
	v_cvt_pk_bf16_f32 v9, v6, v7
	global_store_dwordx2 v[10:11], v[8:9], off
	s_waitcnt vmcnt(26)
	v_lshlrev_b32_e32 v10, 16, v115
	v_and_b32_e32 v11, 0xffff0000, v115
	v_lshlrev_b32_e32 v8, 16, v114
	v_and_b32_e32 v9, 0xffff0000, v114
	s_waitcnt vmcnt(25)
	v_pk_fma_f32 v[2:3], v[2:3], v[6:7], v[10:11]
	v_add_co_u32_e32 v6, vcc, s4, v112
	v_pk_fma_f32 v[0:1], v[0:1], v[4:5], v[8:9]
	s_nop 0
	v_addc_co_u32_e32 v7, vcc, 0, v113, vcc
	v_cvt_pk_bf16_f32 v4, v0, v1
	v_cvt_pk_bf16_f32 v5, v2, v3
	global_store_dwordx2 v[6:7], v[4:5], off
	s_waitcnt vmcnt(25)
	v_lshlrev_b32_e32 v4, 16, v110
	v_and_b32_e32 v5, 0xffff0000, v110
	v_lshlrev_b32_e32 v6, 16, v111
	v_and_b32_e32 v7, 0xffff0000, v111
	s_waitcnt vmcnt(24)
	v_pk_fma_f32 v[0:1], v[52:53], v[0:1], v[4:5]
	v_mul_u32_u24_e32 v4, 33, v175
	v_pk_fma_f32 v[2:3], v[54:55], v[2:3], v[6:7]
	v_ashrrev_i32_e32 v5, 3, v172
	v_lshlrev_b32_e32 v4, 2, v4
	v_lshlrev_b32_e32 v6, 2, v174
	v_add3_u32 v8, 0, v4, v6
	v_add3_u32 v9, 0, v6, v4
	s_movk_i32 s4, 0x84
	v_add_u32_e32 v6, s3, v5
	ds_write_b32 v8, v0
	ds_write2_b32 v9, v1, v2 offset0:33 offset1:66
	ds_write_b32 v9, v3 offset:396
	v_mul_lo_u32 v0, v5, s4
	v_lshlrev_b32_e32 v1, 2, v173
	v_ashrrev_i32_e32 v7, 31, v6
	v_mov_b32_e32 v5, 0xc0
	v_and_b32_e32 v4, 0x70, v1
	v_mad_i64_i32 v[12:13], s[4:5], s2, v5, v[6:7]
	s_movk_i32 s3, 0x600
	v_mov_b64_e32 v[14:15], s[26:27]
	v_add3_u32 v10, 0, v0, v4
	v_mad_u64_u32 v[14:15], s[4:5], v12, s3, v[14:15]
	s_ashr_i32 s23, s22, 31
	s_waitcnt lgkmcnt(0)
	s_barrier
	ds_read2_b32 v[0:1], v10 offset1:1
	ds_read2_b32 v[2:3], v10 offset0:2 offset1:3
	v_mad_i32_i24 v15, v13, s3, v15
	s_lshl_b64 s[4:5], s[22:23], 2
	v_lshl_add_u64 v[12:13], v[14:15], 0, s[4:5]
	v_mov_b32_e32 v5, 0
	v_lshl_add_u64 v[4:5], v[12:13], 0, v[4:5]
	s_mov_b32 s6, 0x164c0000
	v_add_co_u32_e32 v4, vcc, s6, v4
	v_readfirstlane_b32 s35, v105
	s_nop 0
	v_addc_co_u32_e32 v5, vcc, 0, v5, vcc
	s_waitcnt lgkmcnt(0)
	global_store_dwordx4 v[4:5], v[0:3], off
	v_lshl_add_u64 v[4:5], s[20:21], 0, v[106:107]
	v_readfirstlane_b32 s34, v104
	v_mad_i64_i32 v[0:1], s[6:7], v6, s3, 0
	v_mov_b32_e32 v2, 0x48000
	v_mad_i64_i32 v[0:1], s[2:3], s2, v2, v[0:1]
	v_and_b32_e32 v2, 7, v172
	v_lshl_or_b32 v0, v2, 4, v0
	v_lshl_add_u64 v[2:3], v[0:1], 0, s[4:5]
	v_lshl_add_u64 v[0:1], s[26:27], 0, v[2:3]
	s_mov_b64 s[2:3], 0x17bec000
	v_lshl_add_u64 v[0:1], v[0:1], 0, s[2:3]
	s_mov_b64 s[2:3], 0x388a0000
	v_lshl_add_u64 v[4:5], v[4:5], 0, s[2:3]
	v_lshl_add_u64 v[6:7], s[20:21], 0, v[108:109]
	s_mov_b64 s[2:3], 0x33740000
	v_lshl_add_u64 v[2:3], s[34:35], 0, v[2:3]
	v_lshl_add_u64 v[6:7], v[6:7], 0, s[2:3]
	s_mov_b64 s[20:21], 0
	s_barrier
	v_lshl_add_u64 v[38:39], v[2:3], 0, s[20:21]
	global_load_dwordx4 v[34:37], v[38:39], off
	global_load_dwordx2 v[40:41], v[6:7], off
	global_load_dwordx2 v[28:29], v[6:7], off
	global_load_dwordx4 v[30:33], v[4:5], off
	global_load_dwordx2 v[40:41], v[6:7], off
.LBB0_4206:
	s_mov_b64 s[2:3], 0xc00
	s_add_u32 s98, s20, 0x120000
	s_addc_u32 s99, s21, 0
	s_cmp_eq_u32 s98, 0x900000
	s_cselect_b32 s98, s20, s98
	s_cselect_b32 s99, s21, s99
	s_waitcnt vmcnt(4)
	ds_write2_b32 v10, v34, v35 offset1:1
	ds_write2_b32 v10, v36, v37 offset0:2 offset1:3
	s_waitcnt lgkmcnt(0)
	s_barrier
	ds_read_b32 v16, v8
	ds_read2_b32 v[18:19], v9 offset0:33 offset1:66
	ds_read_b32 v21, v9 offset:396
	v_lshl_add_u64 v[38:39], v[2:3], 0, s[98:99]
	global_load_dwordx4 v[34:37], v[38:39], off
	s_waitcnt lgkmcnt(1)
	v_mov_b32_e32 v20, v19
	v_mov_b32_e32 v17, v18
	s_waitcnt vmcnt(3)
	v_lshlrev_b32_e32 v22, 16, v28
	v_and_b32_e32 v23, 0xffff0000, v28
	v_lshlrev_b32_e32 v24, 16, v29
	v_and_b32_e32 v25, 0xffff0000, v29
	v_cvt_pk_bf16_f32 v26, v16, v18
	s_waitcnt lgkmcnt(0)
	v_cvt_pk_bf16_f32 v27, v19, v21
	global_store_dwordx2 v[6:7], v[26:27], off
	s_barrier
	v_lshl_add_u64 v[4:5], v[4:5], 0, s[2:3]
	s_mov_b64 s[2:3], 0x90000
	v_lshl_add_u64 v[6:7], v[6:7], 0, s[2:3]
	global_load_dwordx2 v[28:29], v[6:7], off
	s_waitcnt vmcnt(4)
	v_pk_fma_f32 v[14:15], v[20:21], v[32:33], v[24:25]
	v_pk_fma_f32 v[12:13], v[16:17], v[30:31], v[22:23]
	global_load_dwordx4 v[30:33], v[4:5], off
	ds_write_b32 v8, v12
	ds_write2_b32 v9, v13, v14 offset0:33 offset1:66
	ds_write_b32 v9, v15 offset:396
	s_waitcnt lgkmcnt(0)
	s_barrier
	ds_read2_b32 v[12:13], v10 offset1:1
	ds_read2_b32 v[14:15], v10 offset0:2 offset1:3
	v_lshl_add_u64 v[16:17], v[0:1], 0, s[20:21]
	s_add_u32 s20, s20, 0x120000
	s_addc_u32 s21, s21, 0
	s_cmp_lg_u32 s20, 0x900000
	s_waitcnt lgkmcnt(0)
	global_store_dwordx4 v[16:17], v[12:15], off
	s_barrier
	s_cbranch_scc1 .LBB0_4206
